# code placement: one unreached s_nop after the P7 unit loop so the P7-tail and P9 K-loop heads sit at 0 mod 8 bytes (v47 otherwise)
# speedup vs baseline: 1.0067x; 1.0067x over previous
; #define PG8_GAS __attribute__((address_space(1)))
; __device__ __forceinline__ unsigned cvt_pk_bf16(float lo, float hi) { const f32x2c v = {lo, hi}; return __builtin_bit_cast(unsigned, __builtin_convertvector(v, bf16x2c)); }
; __device__ __forceinline__ float fma_s(float a, float b, float c) { float d; asm("v_fma_f32 %0, %1, %2, %3" : "=v"(d) : "v"(a), "v"(b), "v"(c)); return d; }
; #define PG8_ROR1(x) dpp_ror1(x)
;     __device__ __forceinline__ void run(f32x4 (&acc)[2][2][4][2], const Unit& un, int wr, int wc, int fr, int fq, PG8_LAS unsigned char* xl) const {
;     ...
;             for (int m = 0; m < 4; ++m) { const float iv = __builtin_amdgcn_rsqf(ssq[(size_t)un.pm * BM + wr * 64 + fr + ai * HALF + m * 16] * inv_n + eps);
; #pragma unroll
;                 for (int bj = 0; bj < 2; ++bj)
; #pragma unroll
;                     for (int n = 0; n < 2; ++n) acc[ai][bj][m][n] = acc[ai][bj][m][n] * iv; }
;     ...
;                 for (int m = 0; m < 4; ++m) {
;                     float o[4];
; #pragma unroll
;                     for (int e = 0; e < 4; ++e) {
;                         const float g = acc[ai][0][m][n][e], v = acc[ai][1][m][n][e];
;                         const float gpe = m > 0 ? PG8_ROR1(acc[ai][0][m - 1][n][e]) : hpg[e], vpe = m > 0 ? PG8_ROR1(acc[ai][1][m - 1][n][e]) : hpv[e];
;                         const float gne = m < 3 ? PG8_ROR15(acc[ai][0][m + 1][n][e]) : hng[e], vne = m < 3 ? PG8_ROR15(acc[ai][1][m + 1][n][e]) : hnv[e];
;                         const float gpi = PG8_ROR1(g), vpi = PG8_ROR1(v), gni = PG8_ROR15(g), vni = PG8_ROR15(v);
;                         const float gp = e0 ? gpe : gpi, vp = e0 ? vpe : vpi, gn = e15 ? gne : gni, vn = e15 ? vne : vni;
;                         const float cg = fma_s(w2g[e], gn, fma_s(w1g[e], g, fma_s(w0g[e], gp, bg[e]))), cv = fma_s(w2v[e], vn, fma_s(w1v[e], v, fma_s(w0v[e], vp, bv[e])));
;                         o[e] = (cg * cv) * __builtin_amdgcn_rcpf(1.0f + __builtin_amdgcn_exp2f(cg * -1.4426950408889634f));
;                     }
;                     if (n == 0) { keep[m].x = cvt_pk_bf16(o[0], o[1]); keep[m].y = cvt_pk_bf16(o[2], o[3]); }
;                     else { u32x4 w; w.x = keep[m].x; w.y = keep[m].y; w.z = cvt_pk_bf16(o[0], o[1]); w.w = cvt_pk_bf16(o[2], o[3]);
;                         *(PG8_GAS u32x4*)(act + (size_t)(row0 + ai * HALF + m * 16) * dff + j - 4) = w; }
.LBB0_810:
	v_mov_b32_e32 v115, v114
	v_mov_b32_e32 v117, v116
	v_mov_b32_e32 v84, v114
	v_mov_b32_e32 v85, v114
	v_pk_mul_f32 v[82:83], v[16:17], v[84:85]
	v_pk_mul_f32 v[86:87], v[14:15], v[114:115]
	v_pk_mul_f32 v[8:9], v[8:9], v[84:85]
	v_pk_mul_f32 v[84:85], v[6:7], v[114:115]
	v_mov_b32_e32 v6, v116
	v_mov_b32_e32 v7, v116
	v_pk_mul_f32 v[14:15], v[2:3], v[116:117]
	v_mul_f32_e32 v2, 0xbfb8aa3b, v88
	v_pk_mul_f32 v[16:17], v[10:11], v[116:117]
	v_pk_mul_f32 v[10:11], v[4:5], v[6:7]
	v_exp_f32_e32 v4, v2
	v_mul_f32_e32 v2, 0xbfb8aa3b, v89
	v_pk_mul_f32 v[12:13], v[12:13], v[6:7]
	v_exp_f32_e32 v5, v2
	v_mul_f32_e32 v6, 0xbfb8aa3b, v94
	v_mul_f32_e32 v7, 0xbfb8aa3b, v95
	v_exp_f32_e32 v6, v6
	v_exp_f32_e32 v7, v7
	v_add_f32_e32 v4, 1.0, v4
	v_add_f32_e32 v5, 1.0, v5
	v_rcp_f32_e32 v4, v4
	v_rcp_f32_e32 v5, v5
	v_add_f32_e32 v6, 1.0, v6
	v_add_f32_e32 v7, 1.0, v7
	v_rcp_f32_e32 v6, v6
	v_rcp_f32_e32 v7, v7
	v_pk_mul_f32 v[2:3], v[88:89], v[92:93]
	v_mul_f32_e32 v88, 0xbfb8aa3b, v126
	v_pk_mul_f32 v[2:3], v[2:3], v[4:5]
	v_pk_mul_f32 v[4:5], v[94:95], v[90:91]
	v_cvt_pk_bf16_f32 v3, v2, v3
	v_pk_mul_f32 v[4:5], v[4:5], v[6:7]
	v_mul_f32_e32 v89, 0xbfb8aa3b, v127
	v_cvt_pk_bf16_f32 v2, v4, v5
	v_mul_f32_e32 v4, 0xbfb8aa3b, v130
	v_exp_f32_e32 v6, v4
	v_mul_f32_e32 v4, 0xbfb8aa3b, v131
	v_exp_f32_e32 v7, v4
	v_exp_f32_e32 v88, v88
	v_exp_f32_e32 v89, v89
	v_add_f32_e32 v6, 1.0, v6
	v_add_f32_e32 v7, 1.0, v7
	v_rcp_f32_e32 v6, v6
	v_rcp_f32_e32 v7, v7
	v_add_f32_e32 v88, 1.0, v88
	v_add_f32_e32 v89, 1.0, v89
	v_rcp_f32_e32 v88, v88
	v_rcp_f32_e32 v89, v89
	v_pk_mul_f32 v[4:5], v[130:131], v[132:133]
	v_mul_f32_e32 v90, 0xbfb8aa3b, v118
	v_pk_mul_f32 v[4:5], v[4:5], v[6:7]
	v_pk_mul_f32 v[6:7], v[126:127], v[128:129]
	v_cvt_pk_bf16_f32 v5, v4, v5
	v_pk_mul_f32 v[6:7], v[6:7], v[88:89]
	v_mul_f32_e32 v91, 0xbfb8aa3b, v119
	v_cvt_pk_bf16_f32 v4, v6, v7
	v_mul_f32_e32 v6, 0xbfb8aa3b, v122
	v_exp_f32_e32 v88, v6
	v_mul_f32_e32 v6, 0xbfb8aa3b, v123
	v_exp_f32_e32 v89, v6
	v_exp_f32_e32 v90, v90
	v_exp_f32_e32 v91, v91
	v_add_f32_e32 v88, 1.0, v88
	v_add_f32_e32 v89, 1.0, v89
	v_rcp_f32_e32 v88, v88
	v_rcp_f32_e32 v89, v89
	v_add_f32_e32 v90, 1.0, v90
	v_add_f32_e32 v91, 1.0, v91
	v_rcp_f32_e32 v90, v90
	v_rcp_f32_e32 v91, v91
	v_pk_mul_f32 v[6:7], v[122:123], v[124:125]
	v_mul_f32_e32 v92, 0xbfb8aa3b, v106
	v_pk_mul_f32 v[6:7], v[6:7], v[88:89]
	v_pk_mul_f32 v[88:89], v[118:119], v[120:121]
	v_cvt_pk_bf16_f32 v7, v6, v7
	v_pk_mul_f32 v[88:89], v[88:89], v[90:91]
	v_mul_f32_e32 v93, 0xbfb8aa3b, v107
	v_cvt_pk_bf16_f32 v6, v88, v89
	v_mul_f32_e32 v88, 0xbfb8aa3b, v108
	v_exp_f32_e32 v90, v88
	v_mul_f32_e32 v88, 0xbfb8aa3b, v109
	v_exp_f32_e32 v91, v88
	v_exp_f32_e32 v92, v92
	v_exp_f32_e32 v93, v93
	v_add_f32_e32 v90, 1.0, v90
	v_add_f32_e32 v91, 1.0, v91
	v_rcp_f32_e32 v90, v90
	v_rcp_f32_e32 v91, v91
	v_add_f32_e32 v92, 1.0, v92
	v_add_f32_e32 v93, 1.0, v93
	v_rcp_f32_e32 v92, v92
	v_rcp_f32_e32 v93, v93
	v_pk_mul_f32 v[88:89], v[108:109], v[112:113]
	v_pk_mul_f32 v[88:89], v[88:89], v[90:91]
	v_pk_mul_f32 v[90:91], v[106:107], v[110:111]
	v_cvt_pk_bf16_f32 v89, v88, v89
	v_pk_mul_f32 v[90:91], v[90:91], v[92:93]
	v_cvt_pk_bf16_f32 v88, v90, v91
	s_waitcnt lgkmcnt(1)
	s_waitcnt lgkmcnt(0)
	s_waitcnt lgkmcnt(0)
	v_fma_f32 v179, v58, v38, v66
	s_waitcnt lgkmcnt(0)
	v_fma_f32 v255, v26, v46, v42
	v_fmac_f32_dpp v179, v38, v62 row_shr:1 row_mask:0xf bank_mask:0xf
	v_fma_f32 v181, v59, v39, v67
	v_fma_f32 v185, v27, v47, v43
	v_fmac_f32_dpp v179, v78, v62 row_shl:15 row_mask:0xf bank_mask:0xf
	v_fmac_f32_dpp v255, v46, v34 row_shr:1 row_mask:0xf bank_mask:0xf
	v_fmac_f32_dpp v181, v39, v63 row_shr:1 row_mask:0xf bank_mask:0xf
	v_fmac_f32_dpp v179, v38, v54 row_shl:1 row_mask:0xf bank_mask:0xf
	v_fmac_f32_dpp v255, v74, v34 row_shl:15 row_mask:0xf bank_mask:0xf
	v_fmac_f32_dpp v181, v79, v63 row_shl:15 row_mask:0xf bank_mask:0xf
	v_fmac_f32_dpp v179, v86, v54 row_shr:15 row_mask:0xf bank_mask:0xf
	v_mov_b32_e32 v74, v179
	v_mul_f32_e32 v78, 0xbfb8aa3b, v74
	v_exp_f32_e32 v94, v78
	v_fmac_f32_dpp v255, v46, v30 row_shl:1 row_mask:0xf bank_mask:0xf
	v_add_f32_e32 v90, 1.0, v94
	v_rcp_f32_e32 v90, v90
	v_fmac_f32_dpp v255, v84, v30 row_shr:15 row_mask:0xf bank_mask:0xf
	v_mov_b32_e32 v78, v255
	v_fmac_f32_dpp v181, v39, v55 row_shl:1 row_mask:0xf bank_mask:0xf
	v_fmac_f32_dpp v185, v47, v35 row_shr:1 row_mask:0xf bank_mask:0xf
	v_fma_f32 v183, v60, v40, v68
	v_fma_f32 v179, v28, v48, v44
	v_fmac_f32_dpp v181, v87, v55 row_shr:15 row_mask:0xf bank_mask:0xf
	v_fmac_f32_dpp v185, v75, v35 row_shl:15 row_mask:0xf bank_mask:0xf
	v_mov_b32_e32 v75, v181
	v_mul_f32_e32 v79, 0xbfb8aa3b, v75
	v_exp_f32_e32 v79, v79
	v_fmac_f32_dpp v185, v47, v31 row_shl:1 row_mask:0xf bank_mask:0xf
	v_add_f32_e32 v79, 1.0, v79
	v_rcp_f32_e32 v91, v79
	v_fmac_f32_dpp v185, v85, v31 row_shr:15 row_mask:0xf bank_mask:0xf
	v_mov_b32_e32 v79, v185
	v_pk_mul_f32 v[74:75], v[74:75], v[78:79]
	v_pk_mul_f32 v[74:75], v[74:75], v[90:91]
	v_fmac_f32_dpp v183, v40, v64 row_shr:1 row_mask:0xf bank_mask:0xf
	v_fmac_f32_dpp v179, v48, v36 row_shr:1 row_mask:0xf bank_mask:0xf
	v_fma_f32 v255, v61, v41, v69
	v_fma_f32 v181, v29, v49, v45
	v_fmac_f32_dpp v183, v80, v64 row_shl:15 row_mask:0xf bank_mask:0xf
	v_fmac_f32_dpp v179, v76, v36 row_shl:15 row_mask:0xf bank_mask:0xf
	v_fmac_f32_dpp v255, v41, v65 row_shr:1 row_mask:0xf bank_mask:0xf
	v_fmac_f32_dpp v183, v40, v56 row_shl:1 row_mask:0xf bank_mask:0xf
	v_fmac_f32_dpp v179, v48, v32 row_shl:1 row_mask:0xf bank_mask:0xf
	v_fmac_f32_dpp v255, v81, v65 row_shl:15 row_mask:0xf bank_mask:0xf
	v_fmac_f32_dpp v183, v82, v56 row_shr:15 row_mask:0xf bank_mask:0xf
; #define PG8_GAS __attribute__((address_space(1)))
; __device__ __forceinline__ unsigned cvt_pk_bf16(float lo, float hi) { const f32x2c v = {lo, hi}; return __builtin_bit_cast(unsigned, __builtin_convertvector(v, bf16x2c)); }
; __device__ __forceinline__ float fma_s(float a, float b, float c) { float d; asm("v_fma_f32 %0, %1, %2, %3" : "=v"(d) : "v"(a), "v"(b), "v"(c)); return d; }
; #define PG8_ROR1(x) dpp_ror1(x)
; #define PG8_ROR15(x) dpp_ror15(x)
;     __device__ __forceinline__ void run(f32x4 (&acc)[2][2][4][2], const Unit& un, int wr, int wc, int fr, int fq, PG8_LAS unsigned char* xl) const {
;     ...
;                 for (int m = 0; m < 4; ++m) {
;                     float o[4];
; #pragma unroll
;                     for (int e = 0; e < 4; ++e) {
;                         const float g = acc[ai][0][m][n][e], v = acc[ai][1][m][n][e];
;                         const float gpe = m > 0 ? PG8_ROR1(acc[ai][0][m - 1][n][e]) : hpg[e], vpe = m > 0 ? PG8_ROR1(acc[ai][1][m - 1][n][e]) : hpv[e];
;                         const float gne = m < 3 ? PG8_ROR15(acc[ai][0][m + 1][n][e]) : hng[e], vne = m < 3 ? PG8_ROR15(acc[ai][1][m + 1][n][e]) : hnv[e];
;                         const float gpi = PG8_ROR1(g), vpi = PG8_ROR1(v), gni = PG8_ROR15(g), vni = PG8_ROR15(v);
;                         const float gp = e0 ? gpe : gpi, vp = e0 ? vpe : vpi, gn = e15 ? gne : gni, vn = e15 ? vne : vni;
;                         const float cg = fma_s(w2g[e], gn, fma_s(w1g[e], g, fma_s(w0g[e], gp, bg[e]))), cv = fma_s(w2v[e], vn, fma_s(w1v[e], v, fma_s(w0v[e], vp, bv[e])));
;                         o[e] = (cg * cv) * __builtin_amdgcn_rcpf(1.0f + __builtin_amdgcn_exp2f(cg * -1.4426950408889634f));
;                     }
;                     if (n == 0) { keep[m].x = cvt_pk_bf16(o[0], o[1]); keep[m].y = cvt_pk_bf16(o[2], o[3]); }
;                     else { u32x4 w; w.x = keep[m].x; w.y = keep[m].y; w.z = cvt_pk_bf16(o[0], o[1]); w.w = cvt_pk_bf16(o[2], o[3]);
;                         *(PG8_GAS u32x4*)(act + (size_t)(row0 + ai * HALF + m * 16) * dff + j - 4) = w; }
	v_mov_b32_e32 v76, v183
	v_mul_f32_e32 v78, 0xbfb8aa3b, v76
	v_exp_f32_e32 v90, v78
	v_fmac_f32_dpp v179, v8, v32 row_shr:15 row_mask:0xf bank_mask:0xf
	v_add_f32_e32 v79, 1.0, v90
	v_mov_b32_e32 v78, v179
	v_rcp_f32_e32 v80, v79
	v_fmac_f32_dpp v255, v41, v57 row_shl:1 row_mask:0xf bank_mask:0xf
	v_add_u32_e32 v92, 0x80, v172
	v_fmac_f32_dpp v181, v49, v37 row_shr:1 row_mask:0xf bank_mask:0xf
	v_fmac_f32_dpp v255, v83, v57 row_shr:15 row_mask:0xf bank_mask:0xf
	v_cvt_pk_bf16_f32 v90, v74, v75
	v_fmac_f32_dpp v181, v77, v37 row_shl:15 row_mask:0xf bank_mask:0xf
	v_mov_b32_e32 v77, v255
	v_mul_f32_e32 v79, 0xbfb8aa3b, v77
	v_exp_f32_e32 v79, v79
	v_fmac_f32_dpp v181, v49, v33 row_shl:1 row_mask:0xf bank_mask:0xf
	v_add_f32_e32 v79, 1.0, v79
	v_rcp_f32_e32 v81, v79
	v_fmac_f32_dpp v181, v9, v33 row_shr:15 row_mask:0xf bank_mask:0xf
	v_mov_b32_e32 v79, v181
	v_pk_mul_f32 v[76:77], v[76:77], v[78:79]
	v_pk_mul_f32 v[76:77], v[76:77], v[80:81]
	v_mov_b64_e32 v[74:75], s[24:25]
	v_cvt_pk_bf16_f32 v91, v76, v77
	v_mad_i64_i32 v[76:77], s[14:15], v92, s5, v[74:75]
	v_lshl_add_u64 v[76:77], v[76:77], 0, v[146:147]
	global_store_dwordx4 v[76:77], v[88:91], off
	v_pk_fma_f32 v[250:251], v[26:27], v[84:85], v[42:43]
	v_fma_f32 v185, v58, v86, v66
	v_fma_f32 v183, v59, v87, v67
	v_fmac_f32_dpp v250, v84, v34 row_shr:1 row_mask:0xf bank_mask:0xf
	v_fmac_f32_dpp v251, v85, v35 row_shr:1 row_mask:0xf bank_mask:0xf
	v_fmac_f32_dpp v185, v86, v62 row_shr:1 row_mask:0xf bank_mask:0xf
	v_fmac_f32_dpp v250, v46, v34 row_shl:15 row_mask:0xf bank_mask:0xf
	v_fmac_f32_dpp v251, v47, v35 row_shl:15 row_mask:0xf bank_mask:0xf
	v_fmac_f32_dpp v185, v38, v62 row_shl:15 row_mask:0xf bank_mask:0xf
	v_fmac_f32_dpp v250, v84, v30 row_shl:1 row_mask:0xf bank_mask:0xf
	v_fmac_f32_dpp v251, v85, v31 row_shl:1 row_mask:0xf bank_mask:0xf
	v_fmac_f32_dpp v185, v86, v54 row_shl:1 row_mask:0xf bank_mask:0xf
	v_fmac_f32_dpp v250, v14, v30 row_shr:15 row_mask:0xf bank_mask:0xf
	v_fmac_f32_dpp v251, v15, v31 row_shr:15 row_mask:0xf bank_mask:0xf
	v_mov_b64_e32 v[46:47], v[250:251]
	v_fmac_f32_dpp v185, v16, v54 row_shr:15 row_mask:0xf bank_mask:0xf
	v_mov_b32_e32 v38, v185
	v_mul_f32_e32 v76, 0xbfb8aa3b, v38
	v_fmac_f32_dpp v183, v87, v63 row_shr:1 row_mask:0xf bank_mask:0xf
	v_exp_f32_e32 v76, v76
	v_fma_f32 v179, v60, v82, v68
	v_fmac_f32_dpp v183, v39, v63 row_shl:15 row_mask:0xf bank_mask:0xf
	v_add_f32_e32 v76, 1.0, v76
	v_rcp_f32_e32 v76, v76
	v_fmac_f32_dpp v183, v87, v55 row_shl:1 row_mask:0xf bank_mask:0xf
	v_fmac_f32_dpp v179, v82, v64 row_shr:1 row_mask:0xf bank_mask:0xf
	v_pk_fma_f32 v[252:253], v[28:29], v[8:9], v[44:45]
	v_pk_fma_f32 v[248:249], v[28:29], v[10:11], v[44:45]
	v_pk_fma_f32 v[250:251], v[28:29], v[20:21], v[44:45]
	v_fmac_f32_dpp v183, v17, v55 row_shr:15 row_mask:0xf bank_mask:0xf
	v_mov_b32_e32 v39, v183
	v_mul_f32_e32 v77, 0xbfb8aa3b, v39
	v_exp_f32_e32 v77, v77
	v_pk_mul_f32 v[38:39], v[38:39], v[46:47]
	v_add_f32_e32 v77, 1.0, v77
	v_rcp_f32_e32 v77, v77
	v_fmac_f32_dpp v179, v40, v64 row_shl:15 row_mask:0xf bank_mask:0xf
	v_pk_mul_f32 v[38:39], v[38:39], v[76:77]
	v_fmac_f32_dpp v252, v8, v36 row_shr:1 row_mask:0xf bank_mask:0xf
	v_fmac_f32_dpp v179, v82, v56 row_shl:1 row_mask:0xf bank_mask:0xf
	v_fmac_f32_dpp v253, v9, v37 row_shr:1 row_mask:0xf bank_mask:0xf
	v_fmac_f32_dpp v252, v48, v36 row_shl:15 row_mask:0xf bank_mask:0xf
	v_fmac_f32_dpp v179, v12, v56 row_shr:15 row_mask:0xf bank_mask:0xf
	v_mov_b32_e32 v40, v179
	v_mul_f32_e32 v47, 0xbfb8aa3b, v40
	v_exp_f32_e32 v47, v47
	v_fmac_f32_dpp v253, v49, v37 row_shl:15 row_mask:0xf bank_mask:0xf
	v_add_f32_e32 v46, 1.0, v47
	v_fmac_f32_dpp v252, v8, v32 row_shl:1 row_mask:0xf bank_mask:0xf
	v_fmac_f32_dpp v253, v9, v33 row_shl:1 row_mask:0xf bank_mask:0xf
	v_fma_f32 v255, v61, v83, v69
	v_fmac_f32_dpp v252, v10, v32 row_shr:15 row_mask:0xf bank_mask:0xf
	v_fmac_f32_dpp v253, v11, v33 row_shr:15 row_mask:0xf bank_mask:0xf
	v_fmac_f32_dpp v255, v83, v65 row_shr:1 row_mask:0xf bank_mask:0xf
	v_rcp_f32_e32 v46, v46
	v_fmac_f32_dpp v248, v10, v36 row_shr:1 row_mask:0xf bank_mask:0xf
	v_fmac_f32_dpp v255, v41, v65 row_shl:15 row_mask:0xf bank_mask:0xf
	v_fmac_f32_dpp v249, v11, v37 row_shr:1 row_mask:0xf bank_mask:0xf
	v_fmac_f32_dpp v248, v8, v36 row_shl:15 row_mask:0xf bank_mask:0xf
	v_fmac_f32_dpp v255, v83, v57 row_shl:1 row_mask:0xf bank_mask:0xf
	v_fmac_f32_dpp v249, v9, v37 row_shl:15 row_mask:0xf bank_mask:0xf
	v_mov_b64_e32 v[8:9], v[252:253]
	v_fmac_f32_dpp v255, v13, v57 row_shr:15 row_mask:0xf bank_mask:0xf
	v_mov_b32_e32 v41, v255
	v_pk_mul_f32 v[8:9], v[40:41], v[8:9]
	v_fma_f32 v181, v58, v16, v66
	v_pk_fma_f32 v[252:253], v[26:27], v[14:15], v[42:43]
	v_fmac_f32_dpp v248, v10, v32 row_shl:1 row_mask:0xf bank_mask:0xf
	v_fmac_f32_dpp v181, v16, v62 row_shr:1 row_mask:0xf bank_mask:0xf
	v_fmac_f32_dpp v252, v14, v34 row_shr:1 row_mask:0xf bank_mask:0xf
	v_fmac_f32_dpp v253, v15, v35 row_shr:1 row_mask:0xf bank_mask:0xf
	v_fmac_f32_dpp v181, v86, v62 row_shl:15 row_mask:0xf bank_mask:0xf
	v_fmac_f32_dpp v252, v84, v34 row_shl:15 row_mask:0xf bank_mask:0xf
	v_fmac_f32_dpp v253, v85, v35 row_shl:15 row_mask:0xf bank_mask:0xf
	v_fmac_f32_dpp v181, v16, v54 row_shl:1 row_mask:0xf bank_mask:0xf
	v_fmac_f32_dpp v252, v14, v30 row_shl:1 row_mask:0xf bank_mask:0xf
	v_fmac_f32_dpp v253, v15, v31 row_shl:1 row_mask:0xf bank_mask:0xf
	v_fmac_f32_dpp v181, v22, v54 row_shr:15 row_mask:0xf bank_mask:0xf
	v_fmac_f32_dpp v252, v18, v30 row_shr:15 row_mask:0xf bank_mask:0xf
	v_fmac_f32_dpp v253, v19, v31 row_shr:15 row_mask:0xf bank_mask:0xf
	v_fmac_f32_dpp v249, v11, v33 row_shl:1 row_mask:0xf bank_mask:0xf
; #define PG8_GAS __attribute__((address_space(1)))
; __device__ __forceinline__ unsigned cvt_pk_bf16(float lo, float hi) { const f32x2c v = {lo, hi}; return __builtin_bit_cast(unsigned, __builtin_convertvector(v, bf16x2c)); }
; #define PG8_ROR1(x) dpp_ror1(x)
; #define PG8_ROR15(x) dpp_ror15(x)
; #define PG8_BAR __builtin_amdgcn_s_barrier()
;     __device__ __forceinline__ void run(f32x4 (&acc)[2][2][4][2], const Unit& un, int wr, int wc, int fr, int fq, PG8_LAS unsigned char* xl) const {
;     ...
;                         const float gpe = m > 0 ? PG8_ROR1(acc[ai][0][m - 1][n][e]) : hpg[e], vpe = m > 0 ? PG8_ROR1(acc[ai][1][m - 1][n][e]) : hpv[e];
;                         const float gne = m < 3 ? PG8_ROR15(acc[ai][0][m + 1][n][e]) : hng[e], vne = m < 3 ? PG8_ROR15(acc[ai][1][m + 1][n][e]) : hnv[e];
;                         const float gpi = PG8_ROR1(g), vpi = PG8_ROR1(v), gni = PG8_ROR15(g), vni = PG8_ROR15(v);
;                         const float gp = e0 ? gpe : gpi, vp = e0 ? vpe : vpi, gn = e15 ? gne : gni, vn = e15 ? vne : vni;
;                         const float cg = fma_s(w2g[e], gn, fma_s(w1g[e], g, fma_s(w0g[e], gp, bg[e]))), cv = fma_s(w2v[e], vn, fma_s(w1v[e], v, fma_s(w0v[e], vp, bv[e])));
;                         o[e] = (cg * cv) * __builtin_amdgcn_rcpf(1.0f + __builtin_amdgcn_exp2f(cg * -1.4426950408889634f));
;                     }
;                     if (n == 0) { keep[m].x = cvt_pk_bf16(o[0], o[1]); keep[m].y = cvt_pk_bf16(o[2], o[3]); }
;                     else { u32x4 w; w.x = keep[m].x; w.y = keep[m].y; w.z = cvt_pk_bf16(o[0], o[1]); w.w = cvt_pk_bf16(o[2], o[3]);
;                         *(PG8_GAS u32x4*)(act + (size_t)(row0 + ai * HALF + m * 16) * dff + j - 4) = w; }
; template <class Epi, class Sched, bool ALIGN_EPI = false, bool SP2 = false, bool F8 = false>
; __device__ __forceinline__ void gemm_phase(PG8_LAS unsigned char* lds, const Gemm g, const Sched& S, const Epi& E) {
;     ...
;         if (!has_next) break;
; #pragma unroll
;         for (int a = 0; a < 2; ++a)
; #pragma unroll
;             for (int b = 0; b < 2; ++b)
; #pragma unroll
;                 for (int m = 0; m < 4; ++m)
; #pragma unroll
;                     for (int n = 0; n < 2; ++n) acc[a][b][m][n] = (f32x4){0.f, 0.f, 0.f, 0.f};
;         cur = nxt; cA = nA; cB = nB; ++ui;
;         if constexpr (ALIGN_EPI) { if (wr == 1) PG8_BAR; }
	v_fmac_f32_dpp v248, v20, v32 row_shr:15 row_mask:0xf bank_mask:0xf
	v_fmac_f32_dpp v250, v20, v36 row_shr:1 row_mask:0xf bank_mask:0xf
	v_fmac_f32_dpp v249, v21, v33 row_shr:15 row_mask:0xf bank_mask:0xf
	v_fmac_f32_dpp v251, v21, v37 row_shr:1 row_mask:0xf bank_mask:0xf
	v_fmac_f32_dpp v250, v10, v36 row_shl:15 row_mask:0xf bank_mask:0xf
	v_fma_f32 v185, v59, v17, v67
	v_fmac_f32_dpp v251, v11, v37 row_shl:15 row_mask:0xf bank_mask:0xf
	v_mov_b64_e32 v[10:11], v[248:249]
	v_fmac_f32_dpp v185, v17, v63 row_shr:1 row_mask:0xf bank_mask:0xf
	v_fma_f32 v183, v60, v12, v68
	v_fmac_f32_dpp v250, v20, v32 row_shl:1 row_mask:0xf bank_mask:0xf
	v_fmac_f32_dpp v185, v87, v63 row_shl:15 row_mask:0xf bank_mask:0xf
	v_fmac_f32_dpp v183, v12, v64 row_shr:1 row_mask:0xf bank_mask:0xf
	v_fmac_f32_dpp v251, v21, v33 row_shl:1 row_mask:0xf bank_mask:0xf
	v_fmac_f32_dpp v185, v17, v55 row_shl:1 row_mask:0xf bank_mask:0xf
	v_fmac_f32_dpp v183, v82, v64 row_shl:15 row_mask:0xf bank_mask:0xf
	v_fmac_f32_dpp v250, v52, v32 row_shr:15 row_mask:0xf bank_mask:0xf
	v_fmac_f32_dpp v185, v23, v55 row_shr:15 row_mask:0xf bank_mask:0xf
	v_fmac_f32_dpp v183, v12, v56 row_shl:1 row_mask:0xf bank_mask:0xf
	v_fmac_f32_dpp v251, v53, v33 row_shr:15 row_mask:0xf bank_mask:0xf
	v_fma_f32 v179, v61, v13, v69
	v_fmac_f32_dpp v183, v24, v56 row_shr:15 row_mask:0xf bank_mask:0xf
	v_fma_f32 v255, v58, v22, v66
	v_fmac_f32_dpp v179, v13, v65 row_shr:1 row_mask:0xf bank_mask:0xf
	v_pk_fma_f32 v[248:249], v[26:27], v[18:19], v[42:43]
	v_fmac_f32_dpp v255, v22, v62 row_shr:1 row_mask:0xf bank_mask:0xf
	v_fmac_f32_dpp v179, v83, v65 row_shl:15 row_mask:0xf bank_mask:0xf
	v_mul_f32_e32 v83, 0xbfb8aa3b, v41
	v_exp_f32_e32 v83, v83
	v_fmac_f32_dpp v179, v13, v57 row_shl:1 row_mask:0xf bank_mask:0xf
	v_add_f32_e32 v47, 1.0, v83
	v_rcp_f32_e32 v47, v47
	v_fmac_f32_dpp v179, v25, v57 row_shr:15 row_mask:0xf bank_mask:0xf
	v_pk_mul_f32 v[40:41], v[8:9], v[46:47]
	v_cvt_pk_bf16_f32 v8, v38, v39
	v_add_u32_e32 v38, 0x90, v172
	v_mad_i64_i32 v[38:39], s[14:15], v38, s5, v[74:75]
	v_cvt_pk_bf16_f32 v9, v40, v41
	v_lshl_add_u64 v[38:39], v[38:39], 0, v[146:147]
	global_store_dwordx4 v[38:39], v[6:9], off
	v_fmac_f32_dpp v255, v16, v62 row_shl:15 row_mask:0xf bank_mask:0xf
	v_fmac_f32_dpp v248, v18, v34 row_shr:1 row_mask:0xf bank_mask:0xf
	v_mov_b32_e32 v6, v181
	v_mul_f32_e32 v8, 0xbfb8aa3b, v6
	v_exp_f32_e32 v16, v8
	v_mov_b64_e32 v[8:9], v[252:253]
	v_add_f32_e32 v7, 1.0, v16
	v_rcp_f32_e32 v16, v7
	v_mov_b32_e32 v7, v185
	v_fmac_f32_dpp v255, v22, v54 row_shl:1 row_mask:0xf bank_mask:0xf
	v_fmac_f32_dpp v249, v19, v35 row_shr:1 row_mask:0xf bank_mask:0xf
	v_fmac_f32_dpp v248, v14, v34 row_shl:15 row_mask:0xf bank_mask:0xf
	v_fmac_f32_dpp v255, v70, v54 row_shr:15 row_mask:0xf bank_mask:0xf
	v_fmac_f32_dpp v249, v15, v35 row_shl:15 row_mask:0xf bank_mask:0xf
	v_fmac_f32_dpp v248, v18, v30 row_shl:1 row_mask:0xf bank_mask:0xf
	v_fma_f32 v181, v59, v23, v67
	v_fmac_f32_dpp v249, v19, v31 row_shl:1 row_mask:0xf bank_mask:0xf
	v_fmac_f32_dpp v248, v50, v30 row_shr:15 row_mask:0xf bank_mask:0xf
	v_fmac_f32_dpp v181, v23, v63 row_shr:1 row_mask:0xf bank_mask:0xf
	v_fmac_f32_dpp v249, v51, v31 row_shr:15 row_mask:0xf bank_mask:0xf
	v_fma_f32 v185, v60, v24, v68
	v_fmac_f32_dpp v181, v17, v63 row_shl:15 row_mask:0xf bank_mask:0xf
	v_mul_f32_e32 v17, 0xbfb8aa3b, v7
	v_exp_f32_e32 v17, v17
	v_pk_mul_f32 v[6:7], v[6:7], v[8:9]
	v_add_f32_e32 v17, 1.0, v17
	v_rcp_f32_e32 v17, v17
	v_mov_b32_e32 v8, v183
	v_pk_mul_f32 v[6:7], v[6:7], v[16:17]
	v_cvt_pk_bf16_f32 v6, v6, v7
	v_fmac_f32_dpp v181, v23, v55 row_shl:1 row_mask:0xf bank_mask:0xf
	v_fmac_f32_dpp v185, v24, v64 row_shr:1 row_mask:0xf bank_mask:0xf
	v_fma_f32 v183, v61, v25, v69
	v_fmac_f32_dpp v181, v71, v55 row_shr:15 row_mask:0xf bank_mask:0xf
	v_fmac_f32_dpp v185, v12, v64 row_shl:15 row_mask:0xf bank_mask:0xf
	v_mul_f32_e32 v12, 0xbfb8aa3b, v8
	v_exp_f32_e32 v12, v12
	v_fmac_f32_dpp v185, v24, v56 row_shl:1 row_mask:0xf bank_mask:0xf
	v_add_f32_e32 v9, 1.0, v12
	v_rcp_f32_e32 v12, v9
	v_mov_b32_e32 v9, v179
	v_fmac_f32_dpp v185, v72, v56 row_shr:15 row_mask:0xf bank_mask:0xf
	v_fmac_f32_dpp v183, v25, v65 row_shr:1 row_mask:0xf bank_mask:0xf
	s_nop 0
	s_nop 0
	v_fmac_f32_dpp v183, v13, v65 row_shl:15 row_mask:0xf bank_mask:0xf
	v_mul_f32_e32 v13, 0xbfb8aa3b, v9
	v_exp_f32_e32 v13, v13
	v_pk_mul_f32 v[8:9], v[8:9], v[10:11]
	v_add_f32_e32 v13, 1.0, v13
	v_rcp_f32_e32 v13, v13
	v_fmac_f32_dpp v183, v25, v57 row_shl:1 row_mask:0xf bank_mask:0xf
	v_pk_mul_f32 v[8:9], v[8:9], v[12:13]
	v_cvt_pk_bf16_f32 v7, v8, v9
	v_add_u32_e32 v8, 0xa0, v172
	v_mad_i64_i32 v[8:9], s[14:15], v8, s5, v[74:75]
	v_lshl_add_u64 v[8:9], v[8:9], 0, v[146:147]
	global_store_dwordx4 v[8:9], v[4:7], off
	v_fmac_f32_dpp v183, v73, v57 row_shr:15 row_mask:0xf bank_mask:0xf
	s_nop 0
	v_mov_b32_e32 v4, v255
	v_mul_f32_e32 v6, 0xbfb8aa3b, v4
	v_exp_f32_e32 v8, v6
	v_mov_b64_e32 v[6:7], v[248:249]
	v_add_f32_e32 v5, 1.0, v8
	v_rcp_f32_e32 v8, v5
	v_mov_b32_e32 v5, v181
	v_mul_f32_e32 v9, 0xbfb8aa3b, v5
	v_exp_f32_e32 v9, v9
	v_pk_mul_f32 v[4:5], v[4:5], v[6:7]
	v_add_f32_e32 v9, 1.0, v9
	v_rcp_f32_e32 v9, v9
	v_mov_b32_e32 v6, v185
	v_pk_mul_f32 v[4:5], v[4:5], v[8:9]
	v_mul_f32_e32 v8, 0xbfb8aa3b, v6
	v_exp_f32_e32 v10, v8
	v_mov_b64_e32 v[8:9], v[250:251]
	v_add_f32_e32 v7, 1.0, v10
	v_rcp_f32_e32 v10, v7
	v_cvt_pk_bf16_f32 v4, v4, v5
	v_mov_b32_e32 v7, v183
	v_mul_f32_e32 v11, 0xbfb8aa3b, v7
	v_exp_f32_e32 v11, v11
	v_pk_mul_f32 v[6:7], v[6:7], v[8:9]
	v_add_f32_e32 v11, 1.0, v11
	v_rcp_f32_e32 v11, v11
	s_nop 0
	v_pk_mul_f32 v[6:7], v[6:7], v[10:11]
	v_cvt_pk_bf16_f32 v5, v6, v7
	v_add_u32_e32 v6, 0xb0, v172
	v_mad_i64_i32 v[6:7], s[10:11], v6, s5, v[74:75]
	v_lshl_add_u64 v[6:7], v[6:7], 0, v[146:147]
	global_store_dwordx4 v[6:7], v[2:5], off
	v_mov_b32_e32 v179, 0
	v_mov_b32_e32 v181, 0
	v_mov_b32_e32 v183, 0
	v_mov_b32_e32 v185, 0
	s_andn2_b64 vcc, exec, s[8:9]
	s_mov_b64 s[8:9], -1
	s_cbranch_vccnz .LBB0_766
	s_andn2_b64 vcc, exec, s[30:31]
	s_cbranch_vccnz .LBB0_765
	s_barrier
	s_branch .LBB0_765
	s_nop 0
